# P2 weight-conversion units rewritten by hand: cvt_pk before the LDS transpose, b128 LDS traffic, next tile prefetched; replaces convpf+convnt in the stack
# speedup vs baseline: 1.0314x; 1.0066x over previous
.LBB0_357:
	s_andn2_b64 vcc, exec, s[14:15]
	s_cbranch_vccnz .LBB0_280
	s_cmp_eq_u32 s2, 6
	s_cselect_b32 s4, 1, 0
	s_lshl_b32 s2, s50, 1
	s_add_i32 s2, s2, s4
	s_add_i32 s2, s2, s89
	s_mul_i32 s2, s2, 0x90
	s_add_i32 s2, s2, s76
	s_add_i32 s86, s2, 0x88
	s_load_dwordx2 s[78:79], s[0:1], 0x70
	s_load_dwordx2 s[80:81], s[0:1], 0x80
	s_load_dwordx2 s[82:83], s[0:1], 0x88
	s_load_dwordx2 s[16:17], s[0:1], 0xa0
	v_and_b32_e32 v3, 63, v0
	v_lshrrev_b32_e32 v84, 4, v3
	v_and_b32_e32 v85, 15, v3
	v_lshlrev_b32_e32 v85, 4, v85
	s_mul_i32 s4, s76, 0x2400
	v_mul_u32_u24_e32 v86, 36, v85
	v_lshl_add_u32 v86, v84, 4, v86
	v_add_u32_e32 v86, s4, v86
	v_lshrrev_b32_e32 v87, 3, v3
	v_mul_u32_u24_e32 v87, 0x90, v87
	v_and_b32_e32 v88, 7, v3
	v_lshl_add_u32 v87, v88, 4, v87
	v_add_u32_e32 v87, s4, v87
	v_lshlrev_b32_e32 v88, 4, v3
	s_movk_i32 s41, 9
	s_waitcnt lgkmcnt(0)
	s_mov_b32 s12, s2
	s_mov_b64 s[10:11], s[80:81]
	s_movk_i32 s4, 0x1000
	s_mov_b32 s5, 8
	s_mov_b32 s6, 0x8400000
	s_cmpk_lt_u32 s12, 0x1000
	s_cselect_b64 s[10:11], s[78:79], s[10:11]
	s_cselect_b32 s4, 0, s4
	s_cselect_b32 s5, 6, s5
	s_cselect_b32 s6, 0x6400000, s6
	s_cmpk_lt_u32 s12, 0x5000
	s_cselect_b64 s[10:11], s[10:11], s[82:83]
	s_cselect_b32 s4, s4, 0x5000
	s_cselect_b32 s5, s5, 6
	s_cselect_b32 s6, s6, 0x10400000
	s_cselect_b32 s7, 6, 8
	s_sub_i32 s12, s12, s4
	s_lshr_b32 s4, s12, s5
	s_bfm_b32 s8, s5, 0
	s_and_b32 s12, s12, s8
	s_lshr_b32 s8, s12, 2
	s_lshl_b32 s8, s8, s7
	s_add_i32 s8, s8, s4
	s_lshl_b32 s8, s8, 15
	s_and_b32 s9, s12, 3
	s_lshl_b32 s9, s9, 13
	s_add_i32 s8, s8, s9
	s_add_u32 s8, s8, s6
	s_add_u32 s48, s8, s16
	s_addc_u32 s49, s17, 0
	s_add_i32 s7, s5, 14
	s_lshl_b32 s4, s4, s7
	s_lshl_b32 s12, s12, 8
	s_add_i32 s4, s4, s12
	s_add_u32 s10, s10, s4
	s_addc_u32 s11, s11, 0
	s_add_i32 s7, s5, 8
	s_lshl_b32 s43, 1, s7
	s_mul_i32 s45, s43, 25
	s_lshl_b32 s47, s43, 3
	v_mad_u32_u24 v89, v84, s47, v85
	global_load_dwordx4 v[20:23], v89, s[10:11] nt
	s_add_u32 s10, s10, s43
	s_addc_u32 s11, s11, 0
	global_load_dwordx4 v[24:27], v89, s[10:11] nt
	s_add_u32 s10, s10, s43
	s_addc_u32 s11, s11, 0
	global_load_dwordx4 v[28:31], v89, s[10:11] nt
	s_add_u32 s10, s10, s43
	s_addc_u32 s11, s11, 0
	global_load_dwordx4 v[32:35], v89, s[10:11] nt
	s_add_u32 s10, s10, s43
	s_addc_u32 s11, s11, 0
	global_load_dwordx4 v[36:39], v89, s[10:11] nt
	s_add_u32 s10, s10, s43
	s_addc_u32 s11, s11, 0
	global_load_dwordx4 v[40:43], v89, s[10:11] nt
	s_add_u32 s10, s10, s43
	s_addc_u32 s11, s11, 0
	global_load_dwordx4 v[44:47], v89, s[10:11] nt
	s_add_u32 s10, s10, s43
	s_addc_u32 s11, s11, 0
	global_load_dwordx4 v[48:51], v89, s[10:11] nt
	s_add_u32 s10, s10, s45
	s_addc_u32 s11, s11, 0
	global_load_dwordx4 v[52:55], v89, s[10:11] nt
	s_add_u32 s10, s10, s43
	s_addc_u32 s11, s11, 0
	global_load_dwordx4 v[56:59], v89, s[10:11] nt
	s_add_u32 s10, s10, s43
	s_addc_u32 s11, s11, 0
	global_load_dwordx4 v[60:63], v89, s[10:11] nt
	s_add_u32 s10, s10, s43
	s_addc_u32 s11, s11, 0
	global_load_dwordx4 v[64:67], v89, s[10:11] nt
	s_add_u32 s10, s10, s43
	s_addc_u32 s11, s11, 0
	global_load_dwordx4 v[68:71], v89, s[10:11] nt
	s_add_u32 s10, s10, s43
	s_addc_u32 s11, s11, 0
	global_load_dwordx4 v[72:75], v89, s[10:11] nt
	s_add_u32 s10, s10, s43
	s_addc_u32 s11, s11, 0
	global_load_dwordx4 v[76:79], v89, s[10:11] nt
	s_add_u32 s10, s10, s43
	s_addc_u32 s11, s11, 0
	global_load_dwordx4 v[80:83], v89, s[10:11] nt
.Lcvh_loop:
	s_mov_b64 s[50:51], s[48:49]
	s_add_i32 s2, s2, 8
	s_min_u32 s12, s2, s86
	s_mov_b64 s[10:11], s[80:81]
	s_movk_i32 s4, 0x1000
	s_mov_b32 s5, 8
	s_mov_b32 s6, 0x8400000
	s_cmpk_lt_u32 s12, 0x1000
	s_cselect_b64 s[10:11], s[78:79], s[10:11]
	s_cselect_b32 s4, 0, s4
	s_cselect_b32 s5, 6, s5
	s_cselect_b32 s6, 0x6400000, s6
	s_cmpk_lt_u32 s12, 0x5000
	s_cselect_b64 s[10:11], s[10:11], s[82:83]
	s_cselect_b32 s4, s4, 0x5000
	s_cselect_b32 s5, s5, 6
	s_cselect_b32 s6, s6, 0x10400000
	s_cselect_b32 s7, 6, 8
	s_sub_i32 s12, s12, s4
	s_lshr_b32 s4, s12, s5
	s_bfm_b32 s8, s5, 0
	s_and_b32 s12, s12, s8
	s_lshr_b32 s8, s12, 2
	s_lshl_b32 s8, s8, s7
	s_add_i32 s8, s8, s4
	s_lshl_b32 s8, s8, 15
	s_and_b32 s9, s12, 3
	s_lshl_b32 s9, s9, 13
	s_add_i32 s8, s8, s9
	s_add_u32 s8, s8, s6
	s_add_u32 s48, s8, s16
	s_addc_u32 s49, s17, 0
	s_add_i32 s7, s5, 14
	s_lshl_b32 s4, s4, s7
	s_lshl_b32 s12, s12, 8
	s_add_i32 s4, s4, s12
	s_add_u32 s10, s10, s4
	s_addc_u32 s11, s11, 0
	s_add_i32 s7, s5, 8
	s_lshl_b32 s43, 1, s7
	s_mul_i32 s45, s43, 25
	s_lshl_b32 s47, s43, 3
	v_mad_u32_u24 v89, v84, s47, v85
	global_load_dwordx4 v[100:103], v89, s[10:11] nt
	s_add_u32 s10, s10, s43
	s_addc_u32 s11, s11, 0
	global_load_dwordx4 v[104:107], v89, s[10:11] nt
	s_add_u32 s10, s10, s43
	s_addc_u32 s11, s11, 0
	global_load_dwordx4 v[108:111], v89, s[10:11] nt
	s_add_u32 s10, s10, s43
	s_addc_u32 s11, s11, 0
	global_load_dwordx4 v[112:115], v89, s[10:11] nt
	s_add_u32 s10, s10, s43
	s_addc_u32 s11, s11, 0
	global_load_dwordx4 v[116:119], v89, s[10:11] nt
	s_add_u32 s10, s10, s43
	s_addc_u32 s11, s11, 0
	global_load_dwordx4 v[120:123], v89, s[10:11] nt
	s_add_u32 s10, s10, s43
	s_addc_u32 s11, s11, 0
	global_load_dwordx4 v[124:127], v89, s[10:11] nt
	s_add_u32 s10, s10, s43
	s_addc_u32 s11, s11, 0
	global_load_dwordx4 v[128:131], v89, s[10:11] nt
	s_add_u32 s10, s10, s45
	s_addc_u32 s11, s11, 0
	global_load_dwordx4 v[132:135], v89, s[10:11] nt
	s_add_u32 s10, s10, s43
	s_addc_u32 s11, s11, 0
	global_load_dwordx4 v[136:139], v89, s[10:11] nt
	s_add_u32 s10, s10, s43
	s_addc_u32 s11, s11, 0
	global_load_dwordx4 v[140:143], v89, s[10:11] nt
	s_add_u32 s10, s10, s43
	s_addc_u32 s11, s11, 0
	global_load_dwordx4 v[144:147], v89, s[10:11] nt
	s_add_u32 s10, s10, s43
	s_addc_u32 s11, s11, 0
	global_load_dwordx4 v[148:151], v89, s[10:11] nt
	s_add_u32 s10, s10, s43
	s_addc_u32 s11, s11, 0
	global_load_dwordx4 v[152:155], v89, s[10:11] nt
	s_add_u32 s10, s10, s43
	s_addc_u32 s11, s11, 0
	global_load_dwordx4 v[156:159], v89, s[10:11] nt
	s_add_u32 s10, s10, s43
	s_addc_u32 s11, s11, 0
	global_load_dwordx4 v[160:163], v89, s[10:11] nt
	s_waitcnt vmcnt(16)
	v_cvt_pk_bf16_f32 v164, v20, v24
	v_cvt_pk_bf16_f32 v165, v28, v32
	v_cvt_pk_bf16_f32 v166, v36, v40
	v_cvt_pk_bf16_f32 v167, v44, v48
	ds_write_b128 v86, v[164:167]
	v_cvt_pk_bf16_f32 v168, v21, v25
	v_cvt_pk_bf16_f32 v169, v29, v33
	v_cvt_pk_bf16_f32 v170, v37, v41
	v_cvt_pk_bf16_f32 v171, v45, v49
	ds_write_b128 v86, v[168:171] offset:144
	v_cvt_pk_bf16_f32 v172, v22, v26
	v_cvt_pk_bf16_f32 v173, v30, v34
	v_cvt_pk_bf16_f32 v174, v38, v42
	v_cvt_pk_bf16_f32 v175, v46, v50
	ds_write_b128 v86, v[172:175] offset:288
	v_cvt_pk_bf16_f32 v176, v23, v27
	v_cvt_pk_bf16_f32 v177, v31, v35
	v_cvt_pk_bf16_f32 v178, v39, v43
	v_cvt_pk_bf16_f32 v179, v47, v51
	ds_write_b128 v86, v[176:179] offset:432
	v_cvt_pk_bf16_f32 v180, v52, v56
	v_cvt_pk_bf16_f32 v181, v60, v64
	v_cvt_pk_bf16_f32 v182, v68, v72
	v_cvt_pk_bf16_f32 v183, v76, v80
	ds_write_b128 v86, v[180:183] offset:64
	v_cvt_pk_bf16_f32 v184, v53, v57
	v_cvt_pk_bf16_f32 v185, v61, v65
	v_cvt_pk_bf16_f32 v186, v69, v73
	v_cvt_pk_bf16_f32 v187, v77, v81
	ds_write_b128 v86, v[184:187] offset:208
	v_cvt_pk_bf16_f32 v188, v54, v58
	v_cvt_pk_bf16_f32 v189, v62, v66
	v_cvt_pk_bf16_f32 v190, v70, v74
	v_cvt_pk_bf16_f32 v191, v78, v82
	ds_write_b128 v86, v[188:191] offset:352
	v_cvt_pk_bf16_f32 v192, v55, v59
	v_cvt_pk_bf16_f32 v193, v63, v67
	v_cvt_pk_bf16_f32 v194, v71, v75
	v_cvt_pk_bf16_f32 v195, v79, v83
	ds_write_b128 v86, v[192:195] offset:496
	s_add_u32 s8, s50, 0x1000
	s_addc_u32 s9, s51, 0
	s_waitcnt lgkmcnt(0)
	ds_read_b128 v[164:167], v87
	ds_read_b128 v[168:171], v87 offset:1152
	ds_read_b128 v[172:175], v87 offset:2304
	ds_read_b128 v[176:179], v87 offset:3456
	ds_read_b128 v[180:183], v87 offset:4608
	ds_read_b128 v[184:187], v87 offset:5760
	ds_read_b128 v[188:191], v87 offset:6912
	ds_read_b128 v[192:195], v87 offset:8064
	s_waitcnt lgkmcnt(7)
	global_store_dwordx4 v88, v[164:167], s[50:51] nt
	s_waitcnt lgkmcnt(6)
	global_store_dwordx4 v88, v[168:171], s[50:51] offset:1024 nt
	s_waitcnt lgkmcnt(5)
	global_store_dwordx4 v88, v[172:175], s[50:51] offset:2048 nt
	s_waitcnt lgkmcnt(4)
	global_store_dwordx4 v88, v[176:179], s[50:51] offset:3072 nt
	s_waitcnt lgkmcnt(3)
	global_store_dwordx4 v88, v[180:183], s[8:9] nt
	s_waitcnt lgkmcnt(2)
	global_store_dwordx4 v88, v[184:187], s[8:9] offset:1024 nt
	s_waitcnt lgkmcnt(1)
	global_store_dwordx4 v88, v[188:191], s[8:9] offset:2048 nt
	s_waitcnt lgkmcnt(0)
	global_store_dwordx4 v88, v[192:195], s[8:9] offset:3072 nt
	s_mov_b64 s[50:51], s[48:49]
	s_add_i32 s2, s2, 8
	s_min_u32 s12, s2, s86
	s_mov_b64 s[10:11], s[80:81]
	s_movk_i32 s4, 0x1000
	s_mov_b32 s5, 8
	s_mov_b32 s6, 0x8400000
	s_cmpk_lt_u32 s12, 0x1000
	s_cselect_b64 s[10:11], s[78:79], s[10:11]
	s_cselect_b32 s4, 0, s4
	s_cselect_b32 s5, 6, s5
	s_cselect_b32 s6, 0x6400000, s6
	s_cmpk_lt_u32 s12, 0x5000
	s_cselect_b64 s[10:11], s[10:11], s[82:83]
	s_cselect_b32 s4, s4, 0x5000
	s_cselect_b32 s5, s5, 6
	s_cselect_b32 s6, s6, 0x10400000
	s_cselect_b32 s7, 6, 8
	s_sub_i32 s12, s12, s4
	s_lshr_b32 s4, s12, s5
	s_bfm_b32 s8, s5, 0
	s_and_b32 s12, s12, s8
	s_lshr_b32 s8, s12, 2
	s_lshl_b32 s8, s8, s7
	s_add_i32 s8, s8, s4
	s_lshl_b32 s8, s8, 15
	s_and_b32 s9, s12, 3
	s_lshl_b32 s9, s9, 13
	s_add_i32 s8, s8, s9
	s_add_u32 s8, s8, s6
	s_add_u32 s48, s8, s16
	s_addc_u32 s49, s17, 0
	s_add_i32 s7, s5, 14
	s_lshl_b32 s4, s4, s7
	s_lshl_b32 s12, s12, 8
	s_add_i32 s4, s4, s12
	s_add_u32 s10, s10, s4
	s_addc_u32 s11, s11, 0
	s_add_i32 s7, s5, 8
	s_lshl_b32 s43, 1, s7
	s_mul_i32 s45, s43, 25
	s_lshl_b32 s47, s43, 3
	v_mad_u32_u24 v89, v84, s47, v85
	global_load_dwordx4 v[20:23], v89, s[10:11] nt
	s_add_u32 s10, s10, s43
	s_addc_u32 s11, s11, 0
	global_load_dwordx4 v[24:27], v89, s[10:11] nt
	s_add_u32 s10, s10, s43
	s_addc_u32 s11, s11, 0
	global_load_dwordx4 v[28:31], v89, s[10:11] nt
	s_add_u32 s10, s10, s43
	s_addc_u32 s11, s11, 0
	global_load_dwordx4 v[32:35], v89, s[10:11] nt
	s_add_u32 s10, s10, s43
	s_addc_u32 s11, s11, 0
	global_load_dwordx4 v[36:39], v89, s[10:11] nt
	s_add_u32 s10, s10, s43
	s_addc_u32 s11, s11, 0
	global_load_dwordx4 v[40:43], v89, s[10:11] nt
	s_add_u32 s10, s10, s43
	s_addc_u32 s11, s11, 0
	global_load_dwordx4 v[44:47], v89, s[10:11] nt
	s_add_u32 s10, s10, s43
	s_addc_u32 s11, s11, 0
	global_load_dwordx4 v[48:51], v89, s[10:11] nt
	s_add_u32 s10, s10, s45
	s_addc_u32 s11, s11, 0
	global_load_dwordx4 v[52:55], v89, s[10:11] nt
	s_add_u32 s10, s10, s43
	s_addc_u32 s11, s11, 0
	global_load_dwordx4 v[56:59], v89, s[10:11] nt
	s_add_u32 s10, s10, s43
	s_addc_u32 s11, s11, 0
	global_load_dwordx4 v[60:63], v89, s[10:11] nt
	s_add_u32 s10, s10, s43
	s_addc_u32 s11, s11, 0
	global_load_dwordx4 v[64:67], v89, s[10:11] nt
	s_add_u32 s10, s10, s43
	s_addc_u32 s11, s11, 0
	global_load_dwordx4 v[68:71], v89, s[10:11] nt
	s_add_u32 s10, s10, s43
	s_addc_u32 s11, s11, 0
	global_load_dwordx4 v[72:75], v89, s[10:11] nt
	s_add_u32 s10, s10, s43
	s_addc_u32 s11, s11, 0
	global_load_dwordx4 v[76:79], v89, s[10:11] nt
	s_add_u32 s10, s10, s43
	s_addc_u32 s11, s11, 0
	global_load_dwordx4 v[80:83], v89, s[10:11] nt
	s_waitcnt vmcnt(16)
	v_cvt_pk_bf16_f32 v164, v100, v104
	v_cvt_pk_bf16_f32 v165, v108, v112
	v_cvt_pk_bf16_f32 v166, v116, v120
	v_cvt_pk_bf16_f32 v167, v124, v128
	ds_write_b128 v86, v[164:167]
	v_cvt_pk_bf16_f32 v168, v101, v105
	v_cvt_pk_bf16_f32 v169, v109, v113
	v_cvt_pk_bf16_f32 v170, v117, v121
	v_cvt_pk_bf16_f32 v171, v125, v129
	ds_write_b128 v86, v[168:171] offset:144
	v_cvt_pk_bf16_f32 v172, v102, v106
	v_cvt_pk_bf16_f32 v173, v110, v114
	v_cvt_pk_bf16_f32 v174, v118, v122
	v_cvt_pk_bf16_f32 v175, v126, v130
	ds_write_b128 v86, v[172:175] offset:288
	v_cvt_pk_bf16_f32 v176, v103, v107
	v_cvt_pk_bf16_f32 v177, v111, v115
	v_cvt_pk_bf16_f32 v178, v119, v123
	v_cvt_pk_bf16_f32 v179, v127, v131
	ds_write_b128 v86, v[176:179] offset:432
	v_cvt_pk_bf16_f32 v180, v132, v136
	v_cvt_pk_bf16_f32 v181, v140, v144
	v_cvt_pk_bf16_f32 v182, v148, v152
	v_cvt_pk_bf16_f32 v183, v156, v160
	ds_write_b128 v86, v[180:183] offset:64
	v_cvt_pk_bf16_f32 v184, v133, v137
	v_cvt_pk_bf16_f32 v185, v141, v145
	v_cvt_pk_bf16_f32 v186, v149, v153
	v_cvt_pk_bf16_f32 v187, v157, v161
	ds_write_b128 v86, v[184:187] offset:208
	v_cvt_pk_bf16_f32 v188, v134, v138
	v_cvt_pk_bf16_f32 v189, v142, v146
	v_cvt_pk_bf16_f32 v190, v150, v154
	v_cvt_pk_bf16_f32 v191, v158, v162
	ds_write_b128 v86, v[188:191] offset:352
	v_cvt_pk_bf16_f32 v192, v135, v139
	v_cvt_pk_bf16_f32 v193, v143, v147
	v_cvt_pk_bf16_f32 v194, v151, v155
	v_cvt_pk_bf16_f32 v195, v159, v163
	ds_write_b128 v86, v[192:195] offset:496
	s_add_u32 s8, s50, 0x1000
	s_addc_u32 s9, s51, 0
	s_waitcnt lgkmcnt(0)
	ds_read_b128 v[164:167], v87
	ds_read_b128 v[168:171], v87 offset:1152
	ds_read_b128 v[172:175], v87 offset:2304
	ds_read_b128 v[176:179], v87 offset:3456
	ds_read_b128 v[180:183], v87 offset:4608
	ds_read_b128 v[184:187], v87 offset:5760
	ds_read_b128 v[188:191], v87 offset:6912
	ds_read_b128 v[192:195], v87 offset:8064
	s_waitcnt lgkmcnt(7)
	global_store_dwordx4 v88, v[164:167], s[50:51] nt
	s_waitcnt lgkmcnt(6)
	global_store_dwordx4 v88, v[168:171], s[50:51] offset:1024 nt
	s_waitcnt lgkmcnt(5)
	global_store_dwordx4 v88, v[172:175], s[50:51] offset:2048 nt
	s_waitcnt lgkmcnt(4)
	global_store_dwordx4 v88, v[176:179], s[50:51] offset:3072 nt
	s_waitcnt lgkmcnt(3)
	global_store_dwordx4 v88, v[180:183], s[8:9] nt
	s_waitcnt lgkmcnt(2)
	global_store_dwordx4 v88, v[184:187], s[8:9] offset:1024 nt
	s_waitcnt lgkmcnt(1)
	global_store_dwordx4 v88, v[188:191], s[8:9] offset:2048 nt
	s_waitcnt lgkmcnt(0)
	global_store_dwordx4 v88, v[192:195], s[8:9] offset:3072 nt
	s_add_i32 s41, s41, -1
	s_cmp_lg_u32 s41, 0
	s_cbranch_scc1 .Lcvh_loop
	s_waitcnt vmcnt(0)
	s_branch .LBB0_280
